# k27: k24 + residual epilogues: second-half rows touched by throw-away loads issued after the first-half loads, first-half wait relaxed to vmcnt(8)
# speedup vs baseline: 1.0185x; 1.0185x over previous
.LBB0_587:
	s_lshl_b32 s13, s13, 8
	v_lshl_or_b32 v170, s12, 8, v184
	v_add_u32_e32 v174, s13, v182
	v_ashrrev_i32_e32 v171, 31, v170
	v_lshlrev_b64 v[200:201], 1, v[170:171]
	v_ashrrev_i32_e32 v175, 31, v174
	v_lshl_add_u64 v[172:173], s[78:79], 0, v[200:201]
	v_lshlrev_b64 v[202:203], 11, v[174:175]
	v_lshl_add_u64 v[130:131], v[172:173], 0, v[202:203]
	global_load_dwordx4 v[192:195], v[130:131], off
	global_load_dwordx4 v[196:199], v[130:131], off offset:256
	v_or_b32_e32 v130, 16, v174
	v_or_b32_e32 v132, 32, v174
	v_or_b32_e32 v134, 48, v174
	v_ashrrev_i32_e32 v131, 31, v130
	v_ashrrev_i32_e32 v133, 31, v132
	v_ashrrev_i32_e32 v135, 31, v134
	v_lshlrev_b64 v[180:181], 11, v[130:131]
	v_lshlrev_b64 v[178:179], 11, v[132:133]
	v_lshlrev_b64 v[176:177], 11, v[134:135]
	v_lshl_add_u64 v[130:131], v[172:173], 0, v[180:181]
	v_lshl_add_u64 v[132:133], v[172:173], 0, v[178:179]
	v_lshl_add_u64 v[204:205], v[172:173], 0, v[176:177]
	v_add_co_u32_e32 v230, vcc, 0x38000, v130
	s_nop 1
	v_addc_co_u32_e32 v231, vcc, 0, v131, vcc
	v_add_co_u32_e32 v232, vcc, 0x40000, v130
	s_nop 1
	v_addc_co_u32_e32 v233, vcc, 0, v131, vcc
	v_add_co_u32_e32 v234, vcc, 0x40000, v132
	s_nop 1
	v_addc_co_u32_e32 v235, vcc, 0, v133, vcc
	v_add_co_u32_e32 v236, vcc, 0x40000, v204
	s_nop 1
	v_addc_co_u32_e32 v237, vcc, 0, v205, vcc
	global_load_dwordx4 v[150:153], v[130:131], off
	global_load_dwordx4 v[146:149], v[130:131], off offset:256
	global_load_dwordx4 v[142:145], v[132:133], off
	global_load_dwordx4 v[138:141], v[132:133], off offset:256
	global_load_dwordx4 v[134:137], v[204:205], off
	s_nop 0
	global_load_dwordx4 v[130:133], v[204:205], off offset:256
	global_load_dwordx4 v[246:249], v[230:231], off
	global_load_dwordx4 v[246:249], v[230:231], off offset:256
	global_load_dwordx4 v[246:249], v[232:233], off
	global_load_dwordx4 v[246:249], v[232:233], off offset:256
	global_load_dwordx4 v[246:249], v[234:235], off
	global_load_dwordx4 v[246:249], v[234:235], off offset:256
	global_load_dwordx4 v[246:249], v[236:237], off
	global_load_dwordx4 v[246:249], v[236:237], off offset:256
	v_and_b32_e32 v204, 64, v190
	v_xor_b32_e32 v191, 16, v190
	v_add_u32_e32 v204, 64, v204
	v_xor_b32_e32 v205, 32, v190
	v_cmp_lt_i32_e32 vcc, v191, v204
	v_lshl_add_u64 v[202:203], s[78:79], 0, v[202:203]
	v_lshl_add_u64 v[200:201], v[202:203], 0, v[200:201]
	v_cndmask_b32_e32 v191, v190, v191, vcc
	v_cmp_lt_i32_e32 vcc, v205, v204
	v_lshlrev_b32_e32 v191, 2, v191
	s_waitcnt vmcnt(8) lgkmcnt(15)
	v_lshlrev_b32_e32 v204, 16, v194
	v_cndmask_b32_e32 v210, v190, v205, vcc
	v_and_b32_e32 v205, 0xffff0000, v194
	v_lshlrev_b32_e32 v194, 16, v195
	v_and_b32_e32 v195, 0xffff0000, v195
	v_lshlrev_b32_e32 v202, 16, v192
	v_and_b32_e32 v203, 0xffff0000, v192
	v_lshlrev_b32_e32 v192, 16, v193
	v_and_b32_e32 v193, 0xffff0000, v193
	v_lshlrev_b32_e32 v206, 16, v196
	v_and_b32_e32 v207, 0xffff0000, v196
	v_lshlrev_b32_e32 v196, 16, v197
	v_and_b32_e32 v197, 0xffff0000, v197
	v_lshlrev_b32_e32 v208, 16, v198
	v_and_b32_e32 v209, 0xffff0000, v198
	v_lshlrev_b32_e32 v198, 16, v199
	v_and_b32_e32 v199, 0xffff0000, v199
	v_pk_add_f32 v[124:125], v[124:125], v[194:195]
	v_pk_add_f32 v[122:123], v[122:123], v[204:205]
	v_pk_add_f32 v[126:127], v[126:127], v[202:203]
	v_pk_add_f32 v[128:129], v[128:129], v[192:193]
	v_pk_add_f32 v[120:121], v[120:121], v[196:197]
	v_pk_add_f32 v[194:195], v[116:117], v[198:199]
	v_pk_mul_f32 v[116:117], v[122:123], v[122:123]
	v_pk_mul_f32 v[196:197], v[124:125], v[124:125]
	v_pk_add_f32 v[118:119], v[118:119], v[206:207]
	v_pk_add_f32 v[192:193], v[114:115], v[208:209]
	v_cvt_pk_bf16_f32 v114, v126, v127
	v_cvt_pk_bf16_f32 v115, v128, v129
	v_pk_fma_f32 v[128:129], v[128:129], v[128:129], v[196:197]
	v_pk_fma_f32 v[116:117], v[126:127], v[126:127], v[116:117]
	v_pk_fma_f32 v[126:127], v[120:121], v[120:121], v[128:129]
	v_pk_fma_f32 v[116:117], v[118:119], v[118:119], v[116:117]
	v_pk_fma_f32 v[126:127], v[194:195], v[194:195], v[126:127]
	v_pk_fma_f32 v[116:117], v[192:193], v[192:193], v[116:117]
	s_nop 0
	v_add_f32_e32 v116, v116, v117
	v_add_f32_e32 v117, v126, v127
	v_add_f32_e32 v126, v116, v117
	ds_bpermute_b32 v127, v191, v126
	v_cvt_pk_bf16_f32 v116, v122, v123
	v_cvt_pk_bf16_f32 v117, v124, v125
	global_store_dwordx4 v[200:201], v[114:117], off
	v_cvt_pk_bf16_f32 v118, v118, v119
	v_cvt_pk_bf16_f32 v119, v120, v121
	v_cvt_pk_bf16_f32 v120, v192, v193
	v_cvt_pk_bf16_f32 v121, v194, v195
	global_store_dwordx4 v[200:201], v[118:121], off offset:256
	s_waitcnt lgkmcnt(0)
	v_add_f32_e32 v115, v126, v127
	v_lshlrev_b32_e32 v114, 2, v210
	ds_bpermute_b32 v116, v114, v115
	s_and_saveexec_b64 s[2:3], s[4:5]
	s_cbranch_execz .LBB0_589
	s_waitcnt lgkmcnt(0)
	v_add_f32_e32 v115, v115, v116
	ds_write_b32 v185, v115

.LBB0_923:
	s_lshl_b32 s11, s26, 8
	v_lshl_or_b32 v170, s10, 8, v184
	v_add_u32_e32 v174, s11, v182
	v_ashrrev_i32_e32 v171, 31, v170
	v_lshlrev_b64 v[200:201], 1, v[170:171]
	v_ashrrev_i32_e32 v175, 31, v174
	v_lshl_add_u64 v[172:173], s[78:79], 0, v[200:201]
	v_lshlrev_b64 v[202:203], 11, v[174:175]
	v_lshl_add_u64 v[130:131], v[172:173], 0, v[202:203]
	global_load_dwordx4 v[192:195], v[130:131], off
	global_load_dwordx4 v[196:199], v[130:131], off offset:256
	v_or_b32_e32 v130, 16, v174
	v_or_b32_e32 v132, 32, v174
	v_or_b32_e32 v134, 48, v174
	v_ashrrev_i32_e32 v131, 31, v130
	v_ashrrev_i32_e32 v133, 31, v132
	v_ashrrev_i32_e32 v135, 31, v134
	v_lshlrev_b64 v[180:181], 11, v[130:131]
	v_lshlrev_b64 v[178:179], 11, v[132:133]
	v_lshlrev_b64 v[176:177], 11, v[134:135]
	v_lshl_add_u64 v[130:131], v[172:173], 0, v[180:181]
	v_lshl_add_u64 v[132:133], v[172:173], 0, v[178:179]
	v_lshl_add_u64 v[204:205], v[172:173], 0, v[176:177]
	v_add_co_u32_e32 v230, vcc, 0x38000, v130
	s_nop 1
	v_addc_co_u32_e32 v231, vcc, 0, v131, vcc
	v_add_co_u32_e32 v232, vcc, 0x40000, v130
	s_nop 1
	v_addc_co_u32_e32 v233, vcc, 0, v131, vcc
	v_add_co_u32_e32 v234, vcc, 0x40000, v132
	s_nop 1
	v_addc_co_u32_e32 v235, vcc, 0, v133, vcc
	v_add_co_u32_e32 v236, vcc, 0x40000, v204
	s_nop 1
	v_addc_co_u32_e32 v237, vcc, 0, v205, vcc
	global_load_dwordx4 v[150:153], v[130:131], off
	global_load_dwordx4 v[146:149], v[130:131], off offset:256
	global_load_dwordx4 v[142:145], v[132:133], off
	global_load_dwordx4 v[138:141], v[132:133], off offset:256
	global_load_dwordx4 v[134:137], v[204:205], off
	s_nop 0
	global_load_dwordx4 v[130:133], v[204:205], off offset:256
	global_load_dwordx4 v[246:249], v[230:231], off
	global_load_dwordx4 v[246:249], v[230:231], off offset:256
	global_load_dwordx4 v[246:249], v[232:233], off
	global_load_dwordx4 v[246:249], v[232:233], off offset:256
	global_load_dwordx4 v[246:249], v[234:235], off
	global_load_dwordx4 v[246:249], v[234:235], off offset:256
	global_load_dwordx4 v[246:249], v[236:237], off
	global_load_dwordx4 v[246:249], v[236:237], off offset:256
	v_and_b32_e32 v204, 64, v190
	v_xor_b32_e32 v191, 16, v190
	v_add_u32_e32 v204, 64, v204
	v_xor_b32_e32 v205, 32, v190
	v_cmp_lt_i32_e32 vcc, v191, v204
	v_lshl_add_u64 v[202:203], s[78:79], 0, v[202:203]
	v_lshl_add_u64 v[200:201], v[202:203], 0, v[200:201]
	v_cndmask_b32_e32 v191, v190, v191, vcc
	v_cmp_lt_i32_e32 vcc, v205, v204
	v_lshlrev_b32_e32 v191, 2, v191
	s_waitcnt vmcnt(8) lgkmcnt(15)
	v_lshlrev_b32_e32 v204, 16, v194
	v_cndmask_b32_e32 v210, v190, v205, vcc
	v_and_b32_e32 v205, 0xffff0000, v194
	v_lshlrev_b32_e32 v194, 16, v195
	v_and_b32_e32 v195, 0xffff0000, v195
	v_lshlrev_b32_e32 v202, 16, v192
	v_and_b32_e32 v203, 0xffff0000, v192
	v_lshlrev_b32_e32 v192, 16, v193
	v_and_b32_e32 v193, 0xffff0000, v193
	v_lshlrev_b32_e32 v206, 16, v196
	v_and_b32_e32 v207, 0xffff0000, v196
	v_lshlrev_b32_e32 v196, 16, v197
	v_and_b32_e32 v197, 0xffff0000, v197
	v_lshlrev_b32_e32 v208, 16, v198
	v_and_b32_e32 v209, 0xffff0000, v198
	v_lshlrev_b32_e32 v198, 16, v199
	v_and_b32_e32 v199, 0xffff0000, v199
	v_pk_add_f32 v[124:125], v[124:125], v[194:195]
	v_pk_add_f32 v[122:123], v[122:123], v[204:205]
	v_pk_add_f32 v[126:127], v[126:127], v[202:203]
	v_pk_add_f32 v[128:129], v[128:129], v[192:193]
	v_pk_add_f32 v[120:121], v[120:121], v[196:197]
	v_pk_add_f32 v[194:195], v[116:117], v[198:199]
	v_pk_mul_f32 v[116:117], v[122:123], v[122:123]
	v_pk_mul_f32 v[196:197], v[124:125], v[124:125]
	v_pk_add_f32 v[118:119], v[118:119], v[206:207]
	v_pk_add_f32 v[192:193], v[114:115], v[208:209]
	v_cvt_pk_bf16_f32 v114, v126, v127
	v_cvt_pk_bf16_f32 v115, v128, v129
	v_pk_fma_f32 v[128:129], v[128:129], v[128:129], v[196:197]
	v_pk_fma_f32 v[116:117], v[126:127], v[126:127], v[116:117]
	v_pk_fma_f32 v[126:127], v[120:121], v[120:121], v[128:129]
	v_pk_fma_f32 v[116:117], v[118:119], v[118:119], v[116:117]
	v_pk_fma_f32 v[126:127], v[194:195], v[194:195], v[126:127]
	v_pk_fma_f32 v[116:117], v[192:193], v[192:193], v[116:117]
	s_nop 0
	v_add_f32_e32 v116, v116, v117
	v_add_f32_e32 v117, v126, v127
	v_add_f32_e32 v126, v116, v117
	ds_bpermute_b32 v127, v191, v126
	v_cvt_pk_bf16_f32 v116, v122, v123
	v_cvt_pk_bf16_f32 v117, v124, v125
	global_store_dwordx4 v[200:201], v[114:117], off
	v_cvt_pk_bf16_f32 v118, v118, v119
	v_cvt_pk_bf16_f32 v119, v120, v121
	v_cvt_pk_bf16_f32 v120, v192, v193
	v_cvt_pk_bf16_f32 v121, v194, v195
	global_store_dwordx4 v[200:201], v[118:121], off offset:256
	s_waitcnt lgkmcnt(0)
	v_add_f32_e32 v115, v126, v127
	v_lshlrev_b32_e32 v114, 2, v210
	ds_bpermute_b32 v116, v114, v115
	s_and_saveexec_b64 s[2:3], s[4:5]
	s_cbranch_execz .LBB0_925
	s_waitcnt lgkmcnt(0)
	v_add_f32_e32 v115, v115, v116
	ds_write_b32 v185, v115

.LBB0_1629:
	s_lshl_b32 s11, s36, 8
	v_lshl_or_b32 v170, s10, 8, v183
	v_add_u32_e32 v174, s11, v1
	v_ashrrev_i32_e32 v171, 31, v170
	v_lshlrev_b64 v[200:201], 1, v[170:171]
	v_ashrrev_i32_e32 v175, 31, v174
	v_lshl_add_u64 v[172:173], s[78:79], 0, v[200:201]
	v_lshlrev_b64 v[202:203], 11, v[174:175]
	v_lshl_add_u64 v[130:131], v[172:173], 0, v[202:203]
	global_load_dwordx4 v[192:195], v[130:131], off
	global_load_dwordx4 v[196:199], v[130:131], off offset:256
	v_or_b32_e32 v130, 16, v174
	v_or_b32_e32 v132, 32, v174
	v_or_b32_e32 v134, 48, v174
	v_ashrrev_i32_e32 v131, 31, v130
	v_ashrrev_i32_e32 v133, 31, v132
	v_ashrrev_i32_e32 v135, 31, v134
	v_lshlrev_b64 v[180:181], 11, v[130:131]
	v_lshlrev_b64 v[178:179], 11, v[132:133]
	v_lshlrev_b64 v[176:177], 11, v[134:135]
	v_lshl_add_u64 v[130:131], v[172:173], 0, v[180:181]
	v_lshl_add_u64 v[132:133], v[172:173], 0, v[178:179]
	v_lshl_add_u64 v[190:191], v[172:173], 0, v[176:177]
	v_add_co_u32_e32 v230, vcc, 0x38000, v130
	s_nop 1
	v_addc_co_u32_e32 v231, vcc, 0, v131, vcc
	v_add_co_u32_e32 v232, vcc, 0x40000, v130
	s_nop 1
	v_addc_co_u32_e32 v233, vcc, 0, v131, vcc
	v_add_co_u32_e32 v234, vcc, 0x40000, v132
	s_nop 1
	v_addc_co_u32_e32 v235, vcc, 0, v133, vcc
	v_add_co_u32_e32 v236, vcc, 0x40000, v190
	s_nop 1
	v_addc_co_u32_e32 v237, vcc, 0, v191, vcc
	global_load_dwordx4 v[150:153], v[130:131], off
	global_load_dwordx4 v[146:149], v[130:131], off offset:256
	global_load_dwordx4 v[142:145], v[132:133], off
	global_load_dwordx4 v[138:141], v[132:133], off offset:256
	global_load_dwordx4 v[134:137], v[190:191], off
	s_nop 0
	global_load_dwordx4 v[130:133], v[190:191], off offset:256
	global_load_dwordx4 v[246:249], v[230:231], off
	global_load_dwordx4 v[246:249], v[230:231], off offset:256
	global_load_dwordx4 v[246:249], v[232:233], off
	global_load_dwordx4 v[246:249], v[232:233], off offset:256
	global_load_dwordx4 v[246:249], v[234:235], off
	global_load_dwordx4 v[246:249], v[234:235], off offset:256
	global_load_dwordx4 v[246:249], v[236:237], off
	global_load_dwordx4 v[246:249], v[236:237], off offset:256
	v_and_b32_e32 v191, 64, v189
	v_xor_b32_e32 v190, 16, v189
	v_add_u32_e32 v191, 64, v191
	v_xor_b32_e32 v204, 32, v189
	v_cmp_lt_i32_e32 vcc, v190, v191
	v_lshl_add_u64 v[202:203], s[78:79], 0, v[202:203]
	v_lshl_add_u64 v[200:201], v[202:203], 0, v[200:201]
	v_cndmask_b32_e32 v190, v189, v190, vcc
	v_cmp_lt_i32_e32 vcc, v204, v191
	v_lshlrev_b32_e32 v190, 2, v190
	s_waitcnt vmcnt(8) lgkmcnt(15)
	v_and_b32_e32 v205, 0xffff0000, v194
	v_cndmask_b32_e32 v191, v189, v204, vcc
	v_lshlrev_b32_e32 v204, 16, v194
	v_lshlrev_b32_e32 v194, 16, v195
	v_and_b32_e32 v195, 0xffff0000, v195
	v_lshlrev_b32_e32 v202, 16, v192
	v_and_b32_e32 v203, 0xffff0000, v192
	v_lshlrev_b32_e32 v192, 16, v193
	v_and_b32_e32 v193, 0xffff0000, v193
	v_lshlrev_b32_e32 v206, 16, v196
	v_and_b32_e32 v207, 0xffff0000, v196
	v_lshlrev_b32_e32 v196, 16, v197
	v_and_b32_e32 v197, 0xffff0000, v197
	v_lshlrev_b32_e32 v208, 16, v198
	v_and_b32_e32 v209, 0xffff0000, v198
	v_lshlrev_b32_e32 v198, 16, v199
	v_and_b32_e32 v199, 0xffff0000, v199
	v_pk_add_f32 v[124:125], v[124:125], v[194:195]
	v_pk_add_f32 v[122:123], v[122:123], v[204:205]
	v_pk_add_f32 v[126:127], v[126:127], v[202:203]
	v_pk_add_f32 v[128:129], v[128:129], v[192:193]
	v_pk_add_f32 v[120:121], v[120:121], v[196:197]
	v_pk_add_f32 v[194:195], v[116:117], v[198:199]
	v_pk_mul_f32 v[116:117], v[122:123], v[122:123]
	v_pk_mul_f32 v[196:197], v[124:125], v[124:125]
	v_pk_add_f32 v[118:119], v[118:119], v[206:207]
	v_pk_add_f32 v[192:193], v[114:115], v[208:209]
	v_cvt_pk_bf16_f32 v114, v126, v127
	v_cvt_pk_bf16_f32 v115, v128, v129
	v_pk_fma_f32 v[128:129], v[128:129], v[128:129], v[196:197]
	v_pk_fma_f32 v[116:117], v[126:127], v[126:127], v[116:117]
	v_pk_fma_f32 v[126:127], v[120:121], v[120:121], v[128:129]
	v_pk_fma_f32 v[116:117], v[118:119], v[118:119], v[116:117]
	v_pk_fma_f32 v[126:127], v[194:195], v[194:195], v[126:127]
	v_pk_fma_f32 v[116:117], v[192:193], v[192:193], v[116:117]
	s_nop 0
	v_add_f32_e32 v116, v116, v117
	v_add_f32_e32 v117, v126, v127
	v_add_f32_e32 v126, v116, v117
	ds_bpermute_b32 v127, v190, v126
	v_cvt_pk_bf16_f32 v116, v122, v123
	v_cvt_pk_bf16_f32 v117, v124, v125
	global_store_dwordx4 v[200:201], v[114:117], off
	v_cvt_pk_bf16_f32 v118, v118, v119
	v_cvt_pk_bf16_f32 v119, v120, v121
	v_cvt_pk_bf16_f32 v120, v192, v193
	v_cvt_pk_bf16_f32 v121, v194, v195
	global_store_dwordx4 v[200:201], v[118:121], off offset:256
	s_waitcnt lgkmcnt(0)
	v_add_f32_e32 v115, v126, v127
	v_lshlrev_b32_e32 v114, 2, v191
	ds_bpermute_b32 v116, v114, v115
	s_and_saveexec_b64 s[2:3], s[4:5]
	s_cbranch_execz .LBB0_1631
	s_waitcnt lgkmcnt(0)
	v_add_f32_e32 v115, v115, v116
	ds_write_b32 v184, v115

.LBB0_1844:
	s_lshl_b32 s13, s13, 8
	v_lshl_or_b32 v170, s12, 8, v183
	v_add_u32_e32 v174, s13, v1
	v_ashrrev_i32_e32 v171, 31, v170
	v_lshlrev_b64 v[200:201], 1, v[170:171]
	v_ashrrev_i32_e32 v175, 31, v174
	v_lshl_add_u64 v[172:173], s[78:79], 0, v[200:201]
	v_lshlrev_b64 v[202:203], 11, v[174:175]
	v_lshl_add_u64 v[130:131], v[172:173], 0, v[202:203]
	global_load_dwordx4 v[192:195], v[130:131], off
	global_load_dwordx4 v[196:199], v[130:131], off offset:256
	v_or_b32_e32 v130, 16, v174
	v_or_b32_e32 v132, 32, v174
	v_or_b32_e32 v134, 48, v174
	v_ashrrev_i32_e32 v131, 31, v130
	v_ashrrev_i32_e32 v133, 31, v132
	v_ashrrev_i32_e32 v135, 31, v134
	v_lshlrev_b64 v[180:181], 11, v[130:131]
	v_lshlrev_b64 v[178:179], 11, v[132:133]
	v_lshlrev_b64 v[176:177], 11, v[134:135]
	v_lshl_add_u64 v[130:131], v[172:173], 0, v[180:181]
	v_lshl_add_u64 v[132:133], v[172:173], 0, v[178:179]
	v_lshl_add_u64 v[190:191], v[172:173], 0, v[176:177]
	v_add_co_u32_e32 v230, vcc, 0x38000, v130
	s_nop 1
	v_addc_co_u32_e32 v231, vcc, 0, v131, vcc
	v_add_co_u32_e32 v232, vcc, 0x40000, v130
	s_nop 1
	v_addc_co_u32_e32 v233, vcc, 0, v131, vcc
	v_add_co_u32_e32 v234, vcc, 0x40000, v132
	s_nop 1
	v_addc_co_u32_e32 v235, vcc, 0, v133, vcc
	v_add_co_u32_e32 v236, vcc, 0x40000, v190
	s_nop 1
	v_addc_co_u32_e32 v237, vcc, 0, v191, vcc
	global_load_dwordx4 v[150:153], v[130:131], off
	global_load_dwordx4 v[146:149], v[130:131], off offset:256
	global_load_dwordx4 v[142:145], v[132:133], off
	global_load_dwordx4 v[138:141], v[132:133], off offset:256
	global_load_dwordx4 v[134:137], v[190:191], off
	s_nop 0
	global_load_dwordx4 v[130:133], v[190:191], off offset:256
	global_load_dwordx4 v[246:249], v[230:231], off
	global_load_dwordx4 v[246:249], v[230:231], off offset:256
	global_load_dwordx4 v[246:249], v[232:233], off
	global_load_dwordx4 v[246:249], v[232:233], off offset:256
	global_load_dwordx4 v[246:249], v[234:235], off
	global_load_dwordx4 v[246:249], v[234:235], off offset:256
	global_load_dwordx4 v[246:249], v[236:237], off
	global_load_dwordx4 v[246:249], v[236:237], off offset:256
	v_and_b32_e32 v191, 64, v189
	v_xor_b32_e32 v190, 16, v189
	v_add_u32_e32 v191, 64, v191
	v_xor_b32_e32 v204, 32, v189
	v_cmp_lt_i32_e32 vcc, v190, v191
	v_lshl_add_u64 v[202:203], s[78:79], 0, v[202:203]
	v_lshl_add_u64 v[200:201], v[202:203], 0, v[200:201]
	v_cndmask_b32_e32 v190, v189, v190, vcc
	v_cmp_lt_i32_e32 vcc, v204, v191
	v_lshlrev_b32_e32 v190, 2, v190
	s_waitcnt vmcnt(8) lgkmcnt(15)
	v_and_b32_e32 v205, 0xffff0000, v194
	v_cndmask_b32_e32 v191, v189, v204, vcc
	v_lshlrev_b32_e32 v204, 16, v194
	v_lshlrev_b32_e32 v194, 16, v195
	v_and_b32_e32 v195, 0xffff0000, v195
	v_lshlrev_b32_e32 v202, 16, v192
	v_and_b32_e32 v203, 0xffff0000, v192
	v_lshlrev_b32_e32 v192, 16, v193
	v_and_b32_e32 v193, 0xffff0000, v193
	v_lshlrev_b32_e32 v206, 16, v196
	v_and_b32_e32 v207, 0xffff0000, v196
	v_lshlrev_b32_e32 v196, 16, v197
	v_and_b32_e32 v197, 0xffff0000, v197
	v_lshlrev_b32_e32 v208, 16, v198
	v_and_b32_e32 v209, 0xffff0000, v198
	v_lshlrev_b32_e32 v198, 16, v199
	v_and_b32_e32 v199, 0xffff0000, v199
	v_pk_add_f32 v[124:125], v[124:125], v[194:195]
	v_pk_add_f32 v[122:123], v[122:123], v[204:205]
	v_pk_add_f32 v[126:127], v[126:127], v[202:203]
	v_pk_add_f32 v[128:129], v[128:129], v[192:193]
	v_pk_add_f32 v[120:121], v[120:121], v[196:197]
	v_pk_add_f32 v[194:195], v[116:117], v[198:199]
	v_pk_mul_f32 v[116:117], v[122:123], v[122:123]
	v_pk_mul_f32 v[196:197], v[124:125], v[124:125]
	v_pk_add_f32 v[118:119], v[118:119], v[206:207]
	v_pk_add_f32 v[192:193], v[114:115], v[208:209]
	v_cvt_pk_bf16_f32 v114, v126, v127
	v_cvt_pk_bf16_f32 v115, v128, v129
	v_pk_fma_f32 v[128:129], v[128:129], v[128:129], v[196:197]
	v_pk_fma_f32 v[116:117], v[126:127], v[126:127], v[116:117]
	v_pk_fma_f32 v[126:127], v[120:121], v[120:121], v[128:129]
	v_pk_fma_f32 v[116:117], v[118:119], v[118:119], v[116:117]
	v_pk_fma_f32 v[126:127], v[194:195], v[194:195], v[126:127]
	v_pk_fma_f32 v[116:117], v[192:193], v[192:193], v[116:117]
	s_nop 0
	v_add_f32_e32 v116, v116, v117
	v_add_f32_e32 v117, v126, v127
	v_add_f32_e32 v126, v116, v117
	ds_bpermute_b32 v127, v190, v126
	v_cvt_pk_bf16_f32 v116, v122, v123
	v_cvt_pk_bf16_f32 v117, v124, v125
	global_store_dwordx4 v[200:201], v[114:117], off
	v_cvt_pk_bf16_f32 v118, v118, v119
	v_cvt_pk_bf16_f32 v119, v120, v121
	v_cvt_pk_bf16_f32 v120, v192, v193
	v_cvt_pk_bf16_f32 v121, v194, v195
	global_store_dwordx4 v[200:201], v[118:121], off offset:256
	s_waitcnt lgkmcnt(0)
	v_add_f32_e32 v115, v126, v127
	v_lshlrev_b32_e32 v114, 2, v191
	ds_bpermute_b32 v116, v114, v115
	s_and_saveexec_b64 s[2:3], s[4:5]
	s_cbranch_execz .LBB0_1846
	s_waitcnt lgkmcnt(0)
	v_add_f32_e32 v115, v115, v116
	ds_write_b32 v184, v115
